# work queue: next index fetched in item epilogue, consumed with counted vmcnt (no store drain); plus x loads nt
# speedup vs baseline: 1.0224x; 1.0224x over previous
.LBB0_243:
	s_or_b64 exec, exec, s[0:1]
	s_waitcnt lgkmcnt(0)
	v_mov_b32_e32 v0, v254
	s_barrier
	s_mov_b32 s0, 0x46800000
	v_and_b32_e32 v1, 63, v0
	v_lshlrev_b32_e32 v1, 2, v1
	global_load_dword v2, v1, s[24:25]
	global_load_dword v3, v1, s[26:27]
	global_load_dword v4, v1, s[36:37]
	global_load_dword v5, v1, s[38:39]
	global_load_dword v6, v1, s[20:21]
	global_load_dword v7, v1, s[22:23]
	v_mbcnt_lo_u32_b32 v1, -1, 0
	v_mbcnt_hi_u32_b32 v1, -1, v1
	v_and_b32_e32 v8, 64, v1
	v_xor_b32_e32 v9, 1, v1
	v_add_u32_e32 v8, 64, v8
	v_xor_b32_e32 v10, 2, v1
	v_cmp_lt_i32_e32 vcc, v9, v8
	v_xor_b32_e32 v11, 4, v1
	v_xor_b32_e32 v12, 8, v1
	v_cndmask_b32_e32 v9, v1, v9, vcc
	v_cmp_lt_i32_e32 vcc, v10, v8
	v_xor_b32_e32 v13, 16, v1
	v_xor_b32_e32 v14, 32, v1
	v_cndmask_b32_e32 v10, v1, v10, vcc
	v_cmp_lt_i32_e32 vcc, v11, v8
	s_add_u32 s38, s52, 0x3800000
	s_addc_u32 s44, s53, 0
	v_cndmask_b32_e32 v11, v1, v11, vcc
	v_cmp_lt_i32_e32 vcc, v12, v8
	s_add_u32 s45, s52, 0x4800000
	s_addc_u32 s46, s53, 0
	v_cndmask_b32_e32 v12, v1, v12, vcc
	v_cmp_lt_i32_e32 vcc, v13, v8
	s_add_u32 s47, s52, 0x5800000
	s_addc_u32 s48, s53, 0
	v_cndmask_b32_e32 v13, v1, v13, vcc
	v_cmp_lt_i32_e32 vcc, v14, v8
	v_lshlrev_b32_e32 v8, 2, v9
	v_lshlrev_b32_e32 v9, 2, v10
	v_cndmask_b32_e32 v1, v1, v14, vcc
	v_lshlrev_b32_e32 v10, 2, v11
	v_lshlrev_b32_e32 v11, 2, v12
	v_lshlrev_b32_e32 v193, 2, v13
	v_lshlrev_b32_e32 v194, 2, v1
	s_add_u32 s49, s52, 0x6800000
	s_addc_u32 s50, s53, 0
	s_add_u32 s51, s52, 0x7800000
	s_addc_u32 s56, s53, 0
	s_add_u32 s57, s52, 0x8800000
	s_addc_u32 s58, s53, 0
	s_add_u32 s16, s52, 0xb800000
	s_mov_b32 s21, 0
	s_mov_b32 s39, 0x3fb8aa3b
	s_addc_u32 s17, s53, 0
	v_mov_b32_e32 v131, 0
	s_add_i32 s63, 0, 0x20040
	s_movk_i32 s64, 0x70
	v_mov_b32_e32 v195, 0x358637bd
	s_mov_b32 s65, 0x800000
	s_movk_i32 s66, 0xffef
	s_movk_i32 s67, 0xffe7
	v_mov_b32_e32 v196, 0x3f80
	v_mov_b32_e32 v197, 0x3f803f80
	v_mov_b32_e32 v198, 0x42800000
	v_mov_b32_e32 v199, 0xc6ea6000
	s_waitcnt vmcnt(4)
	v_mul_f32_e32 v1, v2, v3
	ds_bpermute_b32 v1, v8, v1
	s_waitcnt vmcnt(2)
	v_mul_f32_e32 v12, v4, v5
	s_waitcnt vmcnt(1)
	v_and_b32_e32 v13, 0x7fffffff, v6
	s_waitcnt vmcnt(0)
	v_and_b32_e32 v14, 0x7fffffff, v7
	ds_bpermute_b32 v12, v8, v12
	ds_bpermute_b32 v13, v8, v13
	ds_bpermute_b32 v8, v8, v14
	v_max_f32_e64 v6, |v6|, |v6|
	s_waitcnt lgkmcnt(3)
	v_fmac_f32_e32 v1, v2, v3
	s_waitcnt lgkmcnt(2)
	v_fmac_f32_e32 v12, v4, v5
	s_waitcnt lgkmcnt(1)
	v_max_f32_e32 v2, v13, v13
	v_max_f32_e64 v7, |v7|, |v7|
	s_waitcnt lgkmcnt(0)
	v_max_f32_e32 v3, v8, v8
	ds_bpermute_b32 v4, v9, v1
	ds_bpermute_b32 v5, v9, v12
	v_max_f32_e32 v2, v6, v2
	v_max_f32_e32 v3, v7, v3
	ds_bpermute_b32 v6, v9, v2
	ds_bpermute_b32 v7, v9, v3
	s_waitcnt lgkmcnt(3)
	v_add_f32_e32 v1, v1, v4
	s_waitcnt lgkmcnt(2)
	v_add_f32_e32 v4, v12, v5
	ds_bpermute_b32 v5, v10, v1
	ds_bpermute_b32 v8, v10, v4
	s_waitcnt lgkmcnt(3)
	v_max_f32_e32 v6, v6, v6
	s_waitcnt lgkmcnt(2)
	v_max_f32_e32 v7, v7, v7
	v_max_f32_e32 v2, v2, v6
	v_max_f32_e32 v3, v3, v7
	ds_bpermute_b32 v6, v10, v2
	ds_bpermute_b32 v7, v10, v3
	s_waitcnt lgkmcnt(3)
	v_add_f32_e32 v1, v1, v5
	s_waitcnt lgkmcnt(2)
	v_add_f32_e32 v4, v4, v8
	ds_bpermute_b32 v5, v11, v1
	ds_bpermute_b32 v8, v11, v4
	s_waitcnt lgkmcnt(3)
	v_max_f32_e32 v6, v6, v6
	s_waitcnt lgkmcnt(2)
	v_max_f32_e32 v7, v7, v7
	v_max_f32_e32 v2, v2, v6
	v_max_f32_e32 v3, v3, v7
	ds_bpermute_b32 v6, v11, v2
	ds_bpermute_b32 v7, v11, v3
	s_waitcnt lgkmcnt(3)
	v_add_f32_e32 v1, v1, v5
	s_waitcnt lgkmcnt(2)
	v_add_f32_e32 v4, v4, v8
	ds_bpermute_b32 v5, v193, v1
	ds_bpermute_b32 v8, v193, v4
	s_waitcnt lgkmcnt(3)
	v_max_f32_e32 v6, v6, v6
	s_waitcnt lgkmcnt(2)
	v_max_f32_e32 v7, v7, v7
	v_max_f32_e32 v2, v2, v6
	v_max_f32_e32 v3, v3, v7
	ds_bpermute_b32 v6, v193, v2
	ds_bpermute_b32 v7, v193, v3
	s_waitcnt lgkmcnt(3)
	v_add_f32_e32 v1, v1, v5
	s_waitcnt lgkmcnt(2)
	v_add_f32_e32 v4, v4, v8
	ds_bpermute_b32 v5, v194, v1
	ds_bpermute_b32 v8, v194, v4
	s_waitcnt lgkmcnt(3)
	v_max_f32_e32 v6, v6, v6
	s_waitcnt lgkmcnt(2)
	v_max_f32_e32 v7, v7, v7
	v_max_f32_e32 v2, v2, v6
	v_max_f32_e32 v3, v3, v7
	s_waitcnt lgkmcnt(1)
	v_add_f32_e32 v1, v1, v5
	s_waitcnt lgkmcnt(0)
	v_add_f32_e32 v4, v4, v8
	ds_bpermute_b32 v5, v194, v2
	ds_bpermute_b32 v6, v194, v3
	v_mul_f32_e32 v1, 0x3fb8aa3b, v1
	v_mul_f32_e32 v4, 0x3fb8aa3b, v4
	v_exp_f32_e32 v1, v1
	v_exp_f32_e32 v4, v4
	s_waitcnt lgkmcnt(1)
	v_max_f32_e32 v5, v5, v5
	s_waitcnt lgkmcnt(0)
	v_max_f32_e32 v6, v6, v6
	v_max_f32_e32 v2, v2, v5
	v_sub_f32_e32 v1, v1, v4
	v_max_f32_e32 v3, v3, v6
	v_add_f32_e32 v180, 0x3e4ccccd, v1
	v_mul_f32_e32 v1, 0x41000000, v2
	v_mul_f32_e32 v1, v1, v3
	v_mul_f32_e32 v1, 0x3f828f5c, v1
	v_mov_b32_e32 v2, 0x41c80000
	v_fmac_f32_e32 v2, 2.0, v1
	v_mul_f32_e32 v1, 4.0, v2
	v_ceil_f32_e32 v1, v1
	v_mov_b32_e32 v3, 0x46800000
	v_cmp_nle_f32_e32 vcc, s0, v1
	v_mov_b32_e32 v181, v180
	s_nop 0
	v_cndmask_b32_e32 v1, v3, v1, vcc
	s_nop 0
	v_readfirstlane_b32 s59, v1
	v_mul_f32_e32 v1, 0x41800000, v2
	v_ceil_f32_e32 v1, v1
	v_cmp_nle_f32_e32 vcc, s0, v1
	s_nop 1
	v_cndmask_b32_e32 v1, v3, v1, vcc
	s_nop 0
	v_readfirstlane_b32 s60, v1
	v_mul_f32_e32 v1, 0x42800000, v2
	v_ceil_f32_e32 v1, v1
	v_cmp_nle_f32_e32 vcc, s0, v1
	s_nop 1
	v_cndmask_b32_e32 v1, v3, v1, vcc
	s_nop 0
	v_readfirstlane_b32 s61, v1
	v_mul_f32_e32 v1, 0x43800000, v2
	v_ceil_f32_e32 v1, v1
	v_cmp_nle_f32_e32 vcc, s0, v1
	v_cmp_eq_u32_e64 s[0:1], 0, v0
	s_nop 0
	v_cndmask_b32_e32 v1, v3, v1, vcc
	s_nop 0
	v_readfirstlane_b32 s62, v1
	s_and_saveexec_b64 s[4:5], s[0:1]
	v_mov_b32_e32 v255, 1
	global_atomic_add v255, v131, v255, s[52:53] sc0
	s_waitcnt vmcnt(0)
	s_or_b64 exec, exec, s[4:5]
	s_branch .LBB0_246

.LBB0_246:
	s_and_saveexec_b64 s[4:5], s[0:1]
	s_cbranch_execz .LBB0_250
	s_waitcnt vmcnt(8)
	v_mov_b32_e32 v0, v255
	v_mov_b32_e32 v1, s63
	s_nop 0
	ds_write_b32 v1, v0
